# plus: phase-6 state scan spread over all 256 WGs (waves 4-7)
# speedup vs baseline: 1.0271x; 1.0098x over previous
; __device__ __forceinline__ void gl2_scan(PREF p, int gtid, int gthreads) {
;     unsigned* __restrict__ GLS = (unsigned*)(p.ws + WS_GLS); const float* __restrict__ GLD = (const float*)(p.ws + WS_GLD);
;     for (int g = gtid; g < 16 * 4096; g += gthreads) {
;         const int seq = g >> 12, e2 = g & 4095, kk = (e2 * 2) & 63, d = seq & 1;
; __global__ void __launch_bounds__(NTHREADS, 2) mega_fwd(Params p_arg) {
;     ...
;             rg_carry(p, wave, lane);
;             gl2_scan(p, gtid, gthreads);
.LBB0_162:
	s_lshr_b32 s0, s95, 1
	v_add_u32_e32 v82, s0, v52
	v_subrev_u32_e32 v82, 0x100, v82
	v_cmp_lt_u32_e32 vcc, 0xff, v52
	s_and_saveexec_b64 s[4:5], vcc
	s_cbranch_execz .LBB0_167
	s_load_dwordx2 s[0:1], s[38:39], 0xc0
	s_mov_b64 s[10:11], 0
	s_waitcnt lgkmcnt(0)
	s_add_u32 s6, s0, 0x1b000000
	s_addc_u32 s7, s1, 0
	s_add_u32 s8, s0, 0xd00000
	s_addc_u32 s9, s1, 0
